# v071 + 64-byte alignment of the eight hot loop heads (six GEMM K-loops, two attention tile-loop copies)
# speedup vs baseline: 1.0070x; 1.0020x over previous
.LBB0_351:
	s_ashr_i32 s17, s16, 31
	s_lshl_b64 s[24:25], s[16:17], 20
	s_add_u32 s24, s10, s24
	s_addc_u32 s25, s34, s25
	s_and_b64 s[30:31], s[40:41], exec
	s_cselect_b32 s17, s25, s43
	s_cselect_b32 s18, s24, s42
	s_ashr_i32 s5, s4, 31
	s_lshl_b64 s[30:31], s[4:5], 20
	s_add_u32 s30, s26, s30
	s_addc_u32 s31, s27, s31
	s_and_b64 s[52:53], s[40:41], exec
	s_cselect_b32 s5, s31, s45
	s_cselect_b32 s20, s30, s44
	s_add_u32 s42, s42, 0x80080
	s_addc_u32 s43, s43, 0
	s_add_u32 s28, s44, 0x100
	v_mov_b32_e32 v0, 0
	s_addc_u32 s33, s45, 0
	s_mov_b32 s54, -2
	v_mov_b32_e32 v1, v0
	v_mov_b32_e32 v2, v0
	v_mov_b32_e32 v3, v0
	v_mov_b32_e32 v4, v0
	v_mov_b32_e32 v5, v0
	v_mov_b32_e32 v6, v0
	v_mov_b32_e32 v7, v0
	v_mov_b32_e32 v16, v0
	v_mov_b32_e32 v17, v0
	v_mov_b32_e32 v18, v0
	v_mov_b32_e32 v19, v0
	v_mov_b32_e32 v20, v0
	v_mov_b32_e32 v21, v0
	v_mov_b32_e32 v22, v0
	v_mov_b32_e32 v23, v0
	v_mov_b32_e32 v32, v0
	v_mov_b32_e32 v33, v0
	v_mov_b32_e32 v34, v0
	v_mov_b32_e32 v35, v0
	v_mov_b32_e32 v36, v0
	v_mov_b32_e32 v37, v0
	v_mov_b32_e32 v38, v0
	v_mov_b32_e32 v39, v0
	v_mov_b32_e32 v48, v0
	v_mov_b32_e32 v49, v0
	v_mov_b32_e32 v50, v0
	v_mov_b32_e32 v51, v0
	v_mov_b32_e32 v52, v0
	v_mov_b32_e32 v53, v0
	v_mov_b32_e32 v54, v0
	v_mov_b32_e32 v55, v0
	v_mov_b32_e32 v8, v0
	v_mov_b32_e32 v9, v0
	v_mov_b32_e32 v10, v0
	v_mov_b32_e32 v11, v0
	v_mov_b32_e32 v12, v0
	v_mov_b32_e32 v13, v0
	v_mov_b32_e32 v14, v0
	v_mov_b32_e32 v15, v0
	v_mov_b32_e32 v24, v0
	v_mov_b32_e32 v25, v0
	v_mov_b32_e32 v26, v0
	v_mov_b32_e32 v27, v0
	v_mov_b32_e32 v28, v0
	v_mov_b32_e32 v29, v0
	v_mov_b32_e32 v30, v0
	v_mov_b32_e32 v31, v0
	v_mov_b32_e32 v40, v0
	v_mov_b32_e32 v41, v0
	v_mov_b32_e32 v42, v0
	v_mov_b32_e32 v43, v0
	v_mov_b32_e32 v44, v0
	v_mov_b32_e32 v45, v0
	v_mov_b32_e32 v46, v0
	v_mov_b32_e32 v47, v0
	v_mov_b32_e32 v56, v0
	v_mov_b32_e32 v57, v0
	v_mov_b32_e32 v58, v0
	v_mov_b32_e32 v59, v0
	v_mov_b32_e32 v60, v0
	v_mov_b32_e32 v61, v0
	v_mov_b32_e32 v62, v0
	v_mov_b32_e32 v63, v0
	v_mov_b32_e32 v64, v0
	v_mov_b32_e32 v65, v0
	v_mov_b32_e32 v66, v0
	v_mov_b32_e32 v67, v0
	v_mov_b32_e32 v68, v0
	v_mov_b32_e32 v69, v0
	v_mov_b32_e32 v70, v0
	v_mov_b32_e32 v71, v0
	v_mov_b32_e32 v80, v0
	v_mov_b32_e32 v81, v0
	v_mov_b32_e32 v82, v0
	v_mov_b32_e32 v83, v0
	v_mov_b32_e32 v84, v0
	v_mov_b32_e32 v85, v0
	v_mov_b32_e32 v86, v0
	v_mov_b32_e32 v87, v0
	v_mov_b32_e32 v98, v0
	v_mov_b32_e32 v99, v0
	v_mov_b32_e32 v100, v0
	v_mov_b32_e32 v101, v0
	v_mov_b32_e32 v102, v0
	v_mov_b32_e32 v103, v0
	v_mov_b32_e32 v104, v0
	v_mov_b32_e32 v105, v0
	v_mov_b32_e32 v114, v0
	v_mov_b32_e32 v115, v0
	v_mov_b32_e32 v116, v0
	v_mov_b32_e32 v117, v0
	v_mov_b32_e32 v118, v0
	v_mov_b32_e32 v119, v0
	v_mov_b32_e32 v120, v0
	v_mov_b32_e32 v121, v0
	v_mov_b32_e32 v72, v0
	v_mov_b32_e32 v73, v0
	v_mov_b32_e32 v74, v0
	v_mov_b32_e32 v75, v0
	v_mov_b32_e32 v76, v0
	v_mov_b32_e32 v77, v0
	v_mov_b32_e32 v78, v0
	v_mov_b32_e32 v79, v0
	v_mov_b32_e32 v88, v0
	v_mov_b32_e32 v89, v0
	v_mov_b32_e32 v90, v0
	v_mov_b32_e32 v91, v0
	v_mov_b32_e32 v92, v0
	v_mov_b32_e32 v93, v0
	v_mov_b32_e32 v94, v0
	v_mov_b32_e32 v95, v0
	v_mov_b32_e32 v106, v0
	v_mov_b32_e32 v107, v0
	v_mov_b32_e32 v108, v0
	v_mov_b32_e32 v109, v0
	v_mov_b32_e32 v110, v0
	v_mov_b32_e32 v111, v0
	v_mov_b32_e32 v112, v0
	v_mov_b32_e32 v113, v0
	v_mov_b32_e32 v122, v0
	v_mov_b32_e32 v123, v0
	v_mov_b32_e32 v124, v0
	v_mov_b32_e32 v125, v0
	v_mov_b32_e32 v126, v0
	v_mov_b32_e32 v127, v0
	v_mov_b32_e32 v128, v0
	v_mov_b32_e32 v129, v0
	v_add_u32_e32 v154, 0x80, v142
	v_add_u32_e32 v155, 0x80, v138
	v_add_u32_e32 v156, 0x80, v144
	v_add_u32_e32 v157, 0x80, v140
	v_add_u32_e32 v202, 0x80000, v144
	v_add_u32_e32 v203, 0x80000, v140
	.p2align 6

.LBB0_635:
	s_ashr_i32 s43, s42, 31
	s_lshl_b64 s[44:45], s[42:43], 18
	s_add_u32 s44, s2, s44
	s_addc_u32 s45, s3, s45
	s_and_b64 s[50:51], s[40:41], exec
	s_cselect_b32 s35, s45, s69
	s_cselect_b32 s43, s44, s68
	s_ashr_i32 s31, s30, 31
	s_lshl_b64 s[50:51], s[30:31], 18
	s_add_u32 s52, s16, s50
	s_addc_u32 s53, s17, s51
	s_and_b64 s[50:51], s[40:41], exec
	s_cselect_b32 s31, s53, s83
	s_cselect_b32 s50, s52, s82
	s_add_u32 s68, s68, 0x20080
	s_addc_u32 s69, s69, 0
	s_add_u32 s51, s82, 0x100
	v_mov_b32_e32 v0, 0
	s_addc_u32 s54, s83, 0
	s_mov_b32 s55, -2
	v_mov_b32_e32 v1, v0
	v_mov_b32_e32 v2, v0
	v_mov_b32_e32 v3, v0
	v_mov_b32_e32 v4, v0
	v_mov_b32_e32 v5, v0
	v_mov_b32_e32 v6, v0
	v_mov_b32_e32 v7, v0
	v_mov_b32_e32 v8, v0
	v_mov_b32_e32 v9, v0
	v_mov_b32_e32 v10, v0
	v_mov_b32_e32 v11, v0
	v_mov_b32_e32 v12, v0
	v_mov_b32_e32 v13, v0
	v_mov_b32_e32 v14, v0
	v_mov_b32_e32 v15, v0
	v_mov_b32_e32 v24, v0
	v_mov_b32_e32 v25, v0
	v_mov_b32_e32 v26, v0
	v_mov_b32_e32 v27, v0
	v_mov_b32_e32 v28, v0
	v_mov_b32_e32 v29, v0
	v_mov_b32_e32 v30, v0
	v_mov_b32_e32 v31, v0
	v_mov_b32_e32 v40, v0
	v_mov_b32_e32 v41, v0
	v_mov_b32_e32 v42, v0
	v_mov_b32_e32 v43, v0
	v_mov_b32_e32 v44, v0
	v_mov_b32_e32 v45, v0
	v_mov_b32_e32 v46, v0
	v_mov_b32_e32 v47, v0
	v_mov_b32_e32 v16, v0
	v_mov_b32_e32 v17, v0
	v_mov_b32_e32 v18, v0
	v_mov_b32_e32 v19, v0
	v_mov_b32_e32 v20, v0
	v_mov_b32_e32 v21, v0
	v_mov_b32_e32 v22, v0
	v_mov_b32_e32 v23, v0
	v_mov_b32_e32 v32, v0
	v_mov_b32_e32 v33, v0
	v_mov_b32_e32 v34, v0
	v_mov_b32_e32 v35, v0
	v_mov_b32_e32 v36, v0
	v_mov_b32_e32 v37, v0
	v_mov_b32_e32 v38, v0
	v_mov_b32_e32 v39, v0
	v_mov_b32_e32 v48, v0
	v_mov_b32_e32 v49, v0
	v_mov_b32_e32 v50, v0
	v_mov_b32_e32 v51, v0
	v_mov_b32_e32 v52, v0
	v_mov_b32_e32 v53, v0
	v_mov_b32_e32 v54, v0
	v_mov_b32_e32 v55, v0
	v_mov_b32_e32 v56, v0
	v_mov_b32_e32 v57, v0
	v_mov_b32_e32 v58, v0
	v_mov_b32_e32 v59, v0
	v_mov_b32_e32 v60, v0
	v_mov_b32_e32 v61, v0
	v_mov_b32_e32 v62, v0
	v_mov_b32_e32 v63, v0
	v_mov_b32_e32 v64, v0
	v_mov_b32_e32 v65, v0
	v_mov_b32_e32 v66, v0
	v_mov_b32_e32 v67, v0
	v_mov_b32_e32 v68, v0
	v_mov_b32_e32 v69, v0
	v_mov_b32_e32 v70, v0
	v_mov_b32_e32 v71, v0
	v_mov_b32_e32 v72, v0
	v_mov_b32_e32 v73, v0
	v_mov_b32_e32 v74, v0
	v_mov_b32_e32 v75, v0
	v_mov_b32_e32 v76, v0
	v_mov_b32_e32 v77, v0
	v_mov_b32_e32 v78, v0
	v_mov_b32_e32 v79, v0
	v_mov_b32_e32 v88, v0
	v_mov_b32_e32 v89, v0
	v_mov_b32_e32 v90, v0
	v_mov_b32_e32 v91, v0
	v_mov_b32_e32 v92, v0
	v_mov_b32_e32 v93, v0
	v_mov_b32_e32 v94, v0
	v_mov_b32_e32 v95, v0
	v_mov_b32_e32 v106, v0
	v_mov_b32_e32 v107, v0
	v_mov_b32_e32 v108, v0
	v_mov_b32_e32 v109, v0
	v_mov_b32_e32 v110, v0
	v_mov_b32_e32 v111, v0
	v_mov_b32_e32 v112, v0
	v_mov_b32_e32 v113, v0
	v_mov_b32_e32 v80, v0
	v_mov_b32_e32 v81, v0
	v_mov_b32_e32 v82, v0
	v_mov_b32_e32 v83, v0
	v_mov_b32_e32 v84, v0
	v_mov_b32_e32 v85, v0
	v_mov_b32_e32 v86, v0
	v_mov_b32_e32 v87, v0
	v_mov_b32_e32 v98, v0
	v_mov_b32_e32 v99, v0
	v_mov_b32_e32 v100, v0
	v_mov_b32_e32 v101, v0
	v_mov_b32_e32 v102, v0
	v_mov_b32_e32 v103, v0
	v_mov_b32_e32 v104, v0
	v_mov_b32_e32 v105, v0
	v_mov_b32_e32 v114, v0
	v_mov_b32_e32 v115, v0
	v_mov_b32_e32 v116, v0
	v_mov_b32_e32 v117, v0
	v_mov_b32_e32 v118, v0
	v_mov_b32_e32 v119, v0
	v_mov_b32_e32 v120, v0
	v_mov_b32_e32 v121, v0
	v_mov_b32_e32 v122, v0
	v_mov_b32_e32 v123, v0
	v_mov_b32_e32 v124, v0
	v_mov_b32_e32 v125, v0
	v_mov_b32_e32 v126, v0
	v_mov_b32_e32 v127, v0
	v_mov_b32_e32 v128, v0
	v_mov_b32_e32 v129, v0
	v_add_u32_e32 v155, 0x80, v96
	v_add_u32_e32 v157, 0x80, v130
	v_add_u32_e32 v199, 0x80, v134
	v_add_u32_e32 v203, 0x80, v132
	.p2align 6

.LBB0_655:
	s_ashr_i32 s43, s42, 31
	s_lshl_b64 s[44:45], s[42:43], 18
	s_add_u32 s44, s10, s44
	s_addc_u32 s45, s12, s45
	s_and_b64 s[52:53], s[40:41], exec
	s_cselect_b32 s43, s45, s69
	s_cselect_b32 s51, s44, s68
	s_ashr_i32 s31, s30, 31
	s_lshl_b64 s[52:53], s[30:31], 18
	s_add_u32 s52, s2, s52
	s_addc_u32 s53, s3, s53
	s_and_b64 s[54:55], s[40:41], exec
	s_cselect_b32 s31, s53, s83
	s_cselect_b32 s54, s52, s82
	s_add_u32 s68, s68, 0x20080
	s_addc_u32 s69, s69, 0
	s_add_u32 s55, s82, 0x100
	v_mov_b32_e32 v0, 0
	s_addc_u32 s56, s83, 0
	s_mov_b32 s57, -2
	v_mov_b32_e32 v1, v0
	v_mov_b32_e32 v2, v0
	v_mov_b32_e32 v3, v0
	v_mov_b32_e32 v4, v0
	v_mov_b32_e32 v5, v0
	v_mov_b32_e32 v6, v0
	v_mov_b32_e32 v7, v0
	v_mov_b32_e32 v8, v0
	v_mov_b32_e32 v9, v0
	v_mov_b32_e32 v10, v0
	v_mov_b32_e32 v11, v0
	v_mov_b32_e32 v12, v0
	v_mov_b32_e32 v13, v0
	v_mov_b32_e32 v14, v0
	v_mov_b32_e32 v15, v0
	v_mov_b32_e32 v24, v0
	v_mov_b32_e32 v25, v0
	v_mov_b32_e32 v26, v0
	v_mov_b32_e32 v27, v0
	v_mov_b32_e32 v28, v0
	v_mov_b32_e32 v29, v0
	v_mov_b32_e32 v30, v0
	v_mov_b32_e32 v31, v0
	v_mov_b32_e32 v40, v0
	v_mov_b32_e32 v41, v0
	v_mov_b32_e32 v42, v0
	v_mov_b32_e32 v43, v0
	v_mov_b32_e32 v44, v0
	v_mov_b32_e32 v45, v0
	v_mov_b32_e32 v46, v0
	v_mov_b32_e32 v47, v0
	v_mov_b32_e32 v16, v0
	v_mov_b32_e32 v17, v0
	v_mov_b32_e32 v18, v0
	v_mov_b32_e32 v19, v0
	v_mov_b32_e32 v20, v0
	v_mov_b32_e32 v21, v0
	v_mov_b32_e32 v22, v0
	v_mov_b32_e32 v23, v0
	v_mov_b32_e32 v32, v0
	v_mov_b32_e32 v33, v0
	v_mov_b32_e32 v34, v0
	v_mov_b32_e32 v35, v0
	v_mov_b32_e32 v36, v0
	v_mov_b32_e32 v37, v0
	v_mov_b32_e32 v38, v0
	v_mov_b32_e32 v39, v0
	v_mov_b32_e32 v48, v0
	v_mov_b32_e32 v49, v0
	v_mov_b32_e32 v50, v0
	v_mov_b32_e32 v51, v0
	v_mov_b32_e32 v52, v0
	v_mov_b32_e32 v53, v0
	v_mov_b32_e32 v54, v0
	v_mov_b32_e32 v55, v0
	v_mov_b32_e32 v56, v0
	v_mov_b32_e32 v57, v0
	v_mov_b32_e32 v58, v0
	v_mov_b32_e32 v59, v0
	v_mov_b32_e32 v60, v0
	v_mov_b32_e32 v61, v0
	v_mov_b32_e32 v62, v0
	v_mov_b32_e32 v63, v0
	v_mov_b32_e32 v64, v0
	v_mov_b32_e32 v65, v0
	v_mov_b32_e32 v66, v0
	v_mov_b32_e32 v67, v0
	v_mov_b32_e32 v68, v0
	v_mov_b32_e32 v69, v0
	v_mov_b32_e32 v70, v0
	v_mov_b32_e32 v71, v0
	v_mov_b32_e32 v72, v0
	v_mov_b32_e32 v73, v0
	v_mov_b32_e32 v74, v0
	v_mov_b32_e32 v75, v0
	v_mov_b32_e32 v76, v0
	v_mov_b32_e32 v77, v0
	v_mov_b32_e32 v78, v0
	v_mov_b32_e32 v79, v0
	v_mov_b32_e32 v88, v0
	v_mov_b32_e32 v89, v0
	v_mov_b32_e32 v90, v0
	v_mov_b32_e32 v91, v0
	v_mov_b32_e32 v92, v0
	v_mov_b32_e32 v93, v0
	v_mov_b32_e32 v94, v0
	v_mov_b32_e32 v95, v0
	v_mov_b32_e32 v106, v0
	v_mov_b32_e32 v107, v0
	v_mov_b32_e32 v108, v0
	v_mov_b32_e32 v109, v0
	v_mov_b32_e32 v110, v0
	v_mov_b32_e32 v111, v0
	v_mov_b32_e32 v112, v0
	v_mov_b32_e32 v113, v0
	v_mov_b32_e32 v80, v0
	v_mov_b32_e32 v81, v0
	v_mov_b32_e32 v82, v0
	v_mov_b32_e32 v83, v0
	v_mov_b32_e32 v84, v0
	v_mov_b32_e32 v85, v0
	v_mov_b32_e32 v86, v0
	v_mov_b32_e32 v87, v0
	v_mov_b32_e32 v98, v0
	v_mov_b32_e32 v99, v0
	v_mov_b32_e32 v100, v0
	v_mov_b32_e32 v101, v0
	v_mov_b32_e32 v102, v0
	v_mov_b32_e32 v103, v0
	v_mov_b32_e32 v104, v0
	v_mov_b32_e32 v105, v0
	v_mov_b32_e32 v114, v0
	v_mov_b32_e32 v115, v0
	v_mov_b32_e32 v116, v0
	v_mov_b32_e32 v117, v0
	v_mov_b32_e32 v118, v0
	v_mov_b32_e32 v119, v0
	v_mov_b32_e32 v120, v0
	v_mov_b32_e32 v121, v0
	v_mov_b32_e32 v122, v0
	v_mov_b32_e32 v123, v0
	v_mov_b32_e32 v124, v0
	v_mov_b32_e32 v125, v0
	v_mov_b32_e32 v126, v0
	v_mov_b32_e32 v127, v0
	v_mov_b32_e32 v128, v0
	v_mov_b32_e32 v129, v0
	v_add_u32_e32 v155, 0x80, v96
	v_add_u32_e32 v157, 0x80, v130
	v_add_u32_e32 v199, 0x80, v134
	v_add_u32_e32 v203, 0x80, v132
	.p2align 6

.LBB0_735:
	s_mov_b32 s68, s78
	s_mov_b64 s[0:1], 0
	v_mbcnt_lo_u32_b32 v137, -1, 0
	v_mbcnt_hi_u32_b32 v137, -1, v137
	s_add_u32 s40, s62, s0
	s_addc_u32 s41, s63, s1
	s_add_u32 s24, s40, 0x2f800000
	s_addc_u32 s25, s41, 0
	s_add_u32 s52, s40, 0x800000
	s_addc_u32 s53, s41, 0
	s_add_u32 s4, s40, 0x880000
	s_addc_u32 s5, s41, 0
	v_sub_co_u32_e64 v0, s[2:3], s42, 1
	s_and_b64 s[2:3], s[2:3], exec
	v_readfirstlane_b32 s2, v0
	s_cselect_b32 s10, 2, s2
	s_and_b64 s[2:3], s[34:35], exec
	s_cselect_b32 s2, s42, s10
	s_cmp_lg_u32 s2, 2
	s_mov_b64 s[16:17], -1
	s_cbranch_scc0 .LBB0_761
	s_andn2_b64 vcc, exec, s[54:55]
	s_cbranch_vccnz .LBB0_760
	s_cmp_eq_u32 s2, 0
	s_cselect_b32 s2, s15, s9
	s_lshl_b32 s14, s2, 8
	v_mbcnt_lo_u32_b32 v56, -1, 0
	v_mbcnt_hi_u32_b32 v56, -1, v56
	s_add_i32 s3, s14, s13
	v_and_b32_e32 v158, 31, v56
	v_or_b32_e32 v96, s3, v158
	v_lshl_add_u64 v[16:17], s[36:37], 0, v[96:97]
	v_mov_b64_e32 v[18:19], s[40:41]
	s_movk_i32 s3, 0xc00
	v_mad_u64_u32 v[18:19], s[16:17], v16, s3, v[18:19]
	v_readlane_b32 s16, v253, 43
	v_readlane_b32 s17, v253, 44
	v_bfe_u32 v159, v56, 5, 1
	v_mad_i32_i24 v19, v17, s3, v19
	s_mov_b32 s17, s80
	v_lshlrev_b64 v[0:1], 7, v[96:97]
	v_lshl_add_u64 v[16:17], v[18:19], 0, s[16:17]
	v_lshlrev_b32_e32 v130, 4, v159
	v_mov_b32_e32 v131, v97
	v_lshl_add_u64 v[2:3], s[52:53], 0, v[0:1]
	v_and_b32_e32 v96, 32, v56
	s_mov_b32 s10, s16
	v_lshl_add_u64 v[26:27], v[16:17], 0, v[130:131]
	s_mov_b64 s[16:17], 0x2ff00000
	v_lshl_add_u64 v[24:25], v[2:3], 0, v[96:97]
	v_lshl_add_u64 v[0:1], s[4:5], 0, v[0:1]
	v_lshl_add_u64 v[30:31], v[26:27], 0, s[16:17]
	v_lshl_add_u64 v[28:29], v[0:1], 0, v[96:97]
	global_load_dwordx4 v[0:3], v[24:25], off
	global_load_dwordx4 v[4:7], v[28:29], off
	global_load_dwordx4 v[8:11], v[24:25], off offset:16
	global_load_dwordx4 v[12:15], v[28:29], off offset:16
	global_load_dwordx4 v[16:19], v[30:31], off offset:320
	global_load_dwordx4 v[20:23], v[30:31], off offset:256
	s_mov_b32 s3, 0x2ff00000
	v_add_co_u32_e32 v26, vcc, s3, v26
	v_and_b32_e32 v131, 63, v56
	s_nop 0
	v_addc_co_u32_e32 v27, vcc, 0, v27, vcc
	global_load_dwordx4 v[126:129], v[26:27], off
	global_load_dwordx4 v[98:101], v[30:31], off offset:224
	global_load_dwordx4 v[122:125], v[30:31], off offset:32
	global_load_dwordx4 v[118:121], v[30:31], off offset:64
	global_load_dwordx4 v[114:117], v[30:31], off offset:96
	global_load_dwordx4 v[110:113], v[30:31], off offset:128
	global_load_dwordx4 v[106:109], v[30:31], off offset:160
	global_load_dwordx4 v[102:105], v[30:31], off offset:192
	v_lshlrev_b32_e32 v57, 4, v131
	v_add_u32_e32 v163, s20, v57
	v_writelane_b32 v253, s10, 43
	s_add_u32 s3, s40, s46
	v_or_b32_e32 v58, 32, v130
	v_writelane_b32 v253, s11, 44
	s_addc_u32 s10, s41, s47
	v_readlane_b32 s12, v253, 38
	s_add_u32 s3, s3, s12
	s_addc_u32 s10, s10, 0
	s_add_u32 s16, s3, 0x33000000
	s_addc_u32 s17, s10, 0
	v_or_b32_e32 v59, 64, v130
	v_or_b32_e32 v62, 0x60, v130
	v_lshlrev_b32_e32 v63, 7, v158
	s_mov_b32 s81, s80
	s_mov_b32 s82, s80
	s_mov_b32 s83, s80
	s_mov_b32 s84, s80
	s_mov_b32 s85, s80
	s_mov_b32 s86, s80
	s_mov_b32 s87, s80
	s_mov_b32 s88, s80
	s_mov_b32 s89, s80
	s_mov_b32 s90, s80
	s_mov_b32 s91, s80
	s_mov_b32 s92, s80
	s_mov_b32 s93, s80
	s_mov_b32 s94, s80
	s_mov_b32 s95, s80
	s_mov_b32 s26, 2
	v_cmp_gt_u32_e64 s[38:39], 32, v131
	v_lshl_add_u32 v160, v158, 2, s19
	v_mov_b32_e32 v161, 0
	s_waitcnt vmcnt(13)
	v_mov_b32_e32 v33, v0
	s_waitcnt vmcnt(12)
	v_mov_b32_e32 v27, v4
	v_mov_b32_e32 v32, v4
	v_mov_b32_e32 v4, v1
	s_waitcnt vmcnt(9)
	v_lshlrev_b32_e32 v43, 16, v16
	s_waitcnt vmcnt(8)
	v_lshlrev_b32_e32 v42, 16, v20
	v_and_b32_e32 v45, 0xffff0000, v16
	v_and_b32_e32 v44, 0xffff0000, v20
	v_mov_b32_e32 v26, v0
	v_mov_b32_e32 v0, v5
	v_mov_b32_e32 v34, v2
	v_mov_b32_e32 v35, v6
	v_mov_b32_e32 v37, v2
	v_mov_b32_e32 v2, v7
	v_lshlrev_b32_e32 v47, 16, v17
	v_lshlrev_b32_e32 v46, 16, v21
	v_and_b32_e32 v17, 0xffff0000, v17
	v_and_b32_e32 v16, 0xffff0000, v21
	v_pk_mul_f32 v[32:33], v[32:33], v[42:43]
	v_pk_mul_f32 v[4:5], v[4:5], v[44:45]
	v_mov_b32_e32 v36, v6
	v_mov_b32_e32 v6, v3
	v_mov_b32_e32 v39, v12
	v_mov_b32_e32 v40, v12
	v_pk_mul_f32 v[26:27], v[26:27], v[42:43]
	v_pk_mul_f32 v[0:1], v[0:1], v[44:45]
	v_pk_mul_f32 v[34:35], v[34:35], v[46:47]
	v_pk_mul_f32 v[2:3], v[2:3], v[16:17]
	v_add_f32_e32 v12, v32, v33
	v_sub_f32_e32 v4, v4, v5
	v_mov_b32_e32 v38, v8
	v_mov_b32_e32 v41, v8
	v_lshlrev_b32_e32 v21, 16, v18
	v_lshlrev_b32_e32 v20, 16, v22
	v_and_b32_e32 v49, 0xffff0000, v18
	v_and_b32_e32 v48, 0xffff0000, v22
	v_pk_mul_f32 v[36:37], v[36:37], v[46:47]
	v_pk_mul_f32 v[6:7], v[6:7], v[16:17]
	v_sub_f32_e32 v8, v26, v27
	v_add_f32_e32 v1, v0, v1
	v_sub_f32_e32 v5, v34, v35
	v_add_f32_e32 v2, v2, v3
	v_cvt_pk_bf16_f32 v0, v8, v4
	v_cvt_pk_bf16_f32 v4, v12, v1
	v_mov_b32_e32 v12, v9
	v_pk_mul_f32 v[16:17], v[38:39], v[20:21]
	v_add_f32_e32 v18, v36, v37
	v_sub_f32_e32 v6, v6, v7
	v_cvt_pk_bf16_f32 v1, v5, v6
	v_cvt_pk_bf16_f32 v5, v18, v2
	v_pk_mul_f32 v[2:3], v[12:13], v[48:49]
	v_sub_f32_e32 v7, v16, v17
	v_sub_f32_e32 v2, v2, v3
	v_mov_b32_e32 v8, v13
	v_cvt_pk_bf16_f32 v2, v7, v2
	v_pk_mul_f32 v[6:7], v[8:9], v[48:49]
	v_lshlrev_b32_e32 v9, 16, v19
	v_lshlrev_b32_e32 v8, 16, v23
	v_mov_b32_e32 v12, v10
	v_mov_b32_e32 v13, v14
	v_pk_mul_f32 v[20:21], v[40:41], v[20:21]
	v_add_f32_e32 v3, v6, v7
	v_pk_mul_f32 v[12:13], v[12:13], v[8:9]
	v_add_f32_e32 v16, v20, v21
	v_cvt_pk_bf16_f32 v6, v16, v3
	v_sub_f32_e32 v3, v12, v13
	v_mov_b32_e32 v12, v14
	v_mov_b32_e32 v13, v10
	v_pk_mul_f32 v[8:9], v[12:13], v[8:9]
	v_mov_b32_e32 v14, v11
	v_add_f32_e32 v7, v8, v9
	v_and_b32_e32 v9, 0xffff0000, v19
	v_and_b32_e32 v8, 0xffff0000, v23
	v_pk_mul_f32 v[12:13], v[14:15], v[8:9]
	v_add_u32_e32 v40, s18, v56
	v_sub_f32_e32 v10, v12, v13
	v_cvt_pk_bf16_f32 v3, v3, v10
	v_mov_b32_e32 v10, v15
	v_pk_mul_f32 v[8:9], v[10:11], v[8:9]
	s_nop 0
	v_add_f32_e32 v8, v8, v9
	v_cvt_pk_bf16_f32 v7, v7, v8
	global_load_dwordx4 v[8:11], v[30:31], off offset:352
	global_load_dwordx4 v[12:15], v[30:31], off offset:288
	global_load_dwordx4 v[16:19], v[24:25], off offset:64
	global_load_dwordx4 v[20:23], v[28:29], off offset:64
	s_nop 0
	global_load_dwordx4 v[24:27], v[24:25], off offset:80
	s_nop 0
	global_load_dwordx4 v[28:31], v[28:29], off offset:80
	ds_write_b128 v163, v[0:3]
	ds_write_b128 v163, v[4:7] offset:2048
	s_waitcnt vmcnt(5)
	v_lshlrev_b32_e32 v1, 16, v8
	s_waitcnt vmcnt(4)
	v_lshlrev_b32_e32 v0, 16, v12
	s_waitcnt vmcnt(3)
	v_mov_b32_e32 v2, v16
	s_waitcnt vmcnt(2)
	v_mov_b32_e32 v3, v20
	v_mov_b32_e32 v4, v20
	v_mov_b32_e32 v5, v16
	v_and_b32_e32 v7, 0xffff0000, v8
	v_and_b32_e32 v6, 0xffff0000, v12
	v_mov_b32_e32 v20, v17
	v_mov_b32_e32 v16, v21
	v_lshlrev_b32_e32 v33, 16, v9
	v_lshlrev_b32_e32 v32, 16, v13
	v_mov_b32_e32 v34, v18
	v_mov_b32_e32 v35, v22
	v_mov_b32_e32 v36, v22
	v_mov_b32_e32 v37, v18
	v_and_b32_e32 v9, 0xffff0000, v9
	v_and_b32_e32 v8, 0xffff0000, v13
	v_mov_b32_e32 v22, v19
	v_mov_b32_e32 v18, v23
	v_pk_mul_f32 v[2:3], v[2:3], v[0:1]
	v_pk_mul_f32 v[0:1], v[4:5], v[0:1]
	v_pk_mul_f32 v[4:5], v[20:21], v[6:7]
	v_pk_mul_f32 v[6:7], v[16:17], v[6:7]
	v_lshlrev_b32_e32 v13, 16, v10
	v_lshlrev_b32_e32 v12, 16, v14
	s_waitcnt vmcnt(1)
	v_mov_b32_e32 v38, v24
	v_pk_mul_f32 v[16:17], v[34:35], v[32:33]
	v_pk_mul_f32 v[22:23], v[22:23], v[8:9]
	v_pk_mul_f32 v[8:9], v[18:19], v[8:9]
	v_sub_f32_e32 v2, v2, v3
	v_add_f32_e32 v1, v0, v1
	v_sub_f32_e32 v0, v4, v5
	v_add_f32_e32 v3, v6, v7
	s_waitcnt vmcnt(0)
	v_mov_b32_e32 v39, v28
	v_pk_mul_f32 v[20:21], v[36:37], v[32:33]
	v_sub_f32_e32 v5, v16, v17
	v_add_f32_e32 v8, v8, v9
	v_cvt_pk_bf16_f32 v0, v2, v0
	v_cvt_pk_bf16_f32 v4, v1, v3
	v_pk_mul_f32 v[2:3], v[38:39], v[12:13]
	v_add_f32_e32 v6, v20, v21
	v_sub_f32_e32 v7, v22, v23
	v_cvt_pk_bf16_f32 v1, v5, v7
	v_cvt_pk_bf16_f32 v5, v6, v8
	v_sub_f32_e32 v8, v2, v3
	v_mov_b32_e32 v2, v28
	v_mov_b32_e32 v3, v24
	v_pk_mul_f32 v[2:3], v[2:3], v[12:13]
	v_and_b32_e32 v7, 0xffff0000, v10
	v_and_b32_e32 v6, 0xffff0000, v14
	v_mov_b32_e32 v28, v25
	v_add_f32_e32 v9, v2, v3
	v_pk_mul_f32 v[2:3], v[28:29], v[6:7]
	v_mov_b32_e32 v24, v29
	v_sub_f32_e32 v2, v2, v3
	v_pk_mul_f32 v[6:7], v[24:25], v[6:7]
	v_cvt_pk_bf16_f32 v2, v8, v2
	v_lshlrev_b32_e32 v8, 16, v15
	v_add_f32_e32 v3, v6, v7
	v_cvt_pk_bf16_f32 v6, v9, v3
	v_lshlrev_b32_e32 v9, 16, v11
	v_mov_b32_e32 v12, v26
	v_mov_b32_e32 v13, v30
	v_pk_mul_f32 v[12:13], v[12:13], v[8:9]
	v_ashrrev_i32_e32 v20, 4, v40
	v_sub_f32_e32 v3, v12, v13
	v_mov_b32_e32 v12, v30
	v_mov_b32_e32 v13, v26
	v_pk_mul_f32 v[8:9], v[12:13], v[8:9]
	v_mov_b32_e32 v30, v27
	v_add_f32_e32 v7, v8, v9
	v_and_b32_e32 v9, 0xffff0000, v11
	v_and_b32_e32 v8, 0xffff0000, v15
	v_pk_mul_f32 v[10:11], v[30:31], v[8:9]
	v_mov_b32_e32 v26, v31
	v_sub_f32_e32 v10, v10, v11
	v_cvt_pk_bf16_f32 v3, v3, v10
	v_pk_mul_f32 v[8:9], v[26:27], v[8:9]
	v_lshlrev_b32_e32 v26, 3, v56
	v_add_f32_e32 v8, v8, v9
	v_cvt_pk_bf16_f32 v7, v7, v8
	ds_write_b128 v163, v[0:3] offset:1024
	ds_write_b128 v163, v[4:7] offset:3072
	v_and_b32_e32 v0, 0x78, v26
	v_ashrrev_i32_e32 v21, 31, v20
	v_lshlrev_b32_e32 v27, 1, v0
	v_lshlrev_b64 v[48:49], 12, v[20:21]
	v_or_b32_e32 v0, v48, v27
	v_mov_b32_e32 v1, v49
	s_waitcnt lgkmcnt(0)
	v_add_u32_e32 v22, 32, v20
	v_lshl_add_u64 v[52:53], s[16:17], 0, v[0:1]
	global_load_dwordx4 v[0:3], v[52:53], off offset:256
	v_ashrrev_i32_e32 v23, 31, v22
	v_lshlrev_b64 v[4:5], 12, v[22:23]
	v_or_b32_e32 v4, v4, v27
	v_ashrrev_i32_e32 v24, 3, v40
	v_lshl_add_u64 v[12:13], s[16:17], 0, v[4:5]
	s_add_u32 s16, s24, s48
	v_ashrrev_i32_e32 v25, 31, v24
	s_addc_u32 s17, s25, s49
	v_lshlrev_b64 v[50:51], 7, v[24:25]
	v_lshlrev_b32_e32 v18, 4, v56
	v_lshl_add_u64 v[16:17], s[16:17], 0, v[50:51]
	v_and_b32_e32 v96, 0x70, v18
	global_load_dwordx4 v[4:7], v[12:13], off offset:256
	global_load_dwordx4 v[8:11], v[52:53], off
	v_lshl_add_u64 v[54:55], v[16:17], 0, v[96:97]
	global_load_dwordx4 v[12:15], v[12:13], off
	v_and_b32_e32 v21, 0xfffff0, v20
	global_load_dwordx4 v[16:19], v[54:55], off
	v_lshlrev_b32_e32 v23, 1, v20
	v_and_or_b32 v21, v23, 8, v21
	v_lshrrev_b32_e32 v23, 1, v20
	v_lshrrev_b32_e32 v21, 1, v21
	v_bfe_u32 v25, v26, 5, 2
	v_and_b32_e32 v26, 3, v20
	v_or_b32_e32 v21, v21, v25
	v_and_or_b32 v23, v23, 4, v26
	v_lshlrev_b32_e32 v21, 9, v21
	v_lshlrev_b32_e32 v23, 6, v23
	v_and_b32_e32 v26, 48, v27
	v_or3_b32 v21, v21, v23, v26
	v_and_b32_e32 v28, 0xfffff0, v22
	v_lshlrev_b32_e32 v29, 1, v22
	v_add_u32_e32 v166, 0, v21
	v_and_or_b32 v28, v29, 8, v28
	s_waitcnt vmcnt(0)
	v_lshrrev_b32_e32 v28, 1, v28
	v_or_b32_e32 v25, v28, v25
	v_lshlrev_b32_e32 v25, 9, v25
	v_or3_b32 v23, v25, v23, v26
	s_cmp_lg_u32 0, -1
	s_cselect_b32 s3, 0, 0
	v_add_u32_e32 v167, 0, v23
	s_add_i32 s12, 0, 0x10000
	v_bitop3_b32 v178, v130, v63, v96 bitop3:0xde
	v_add_u32_e32 v179, s12, v178
	v_bitop3_b32 v180, v58, v63, v96 bitop3:0xde
	v_add_u32_e32 v181, s12, v180
	v_bitop3_b32 v182, v59, v63, v96 bitop3:0xde
	v_add_u32_e32 v183, s12, v182
	v_bitop3_b32 v184, v62, v63, v96 bitop3:0xde
	v_add_u32_e32 v185, s12, v184
	s_lshl_b32 s27, s2, 2
	s_mov_b32 s2, 0x40000
	s_mov_b64 s[16:17], 0x40000
	v_add_co_u32_e32 v66, vcc, s2, v52
	s_mov_b32 s2, 0x60000
	s_nop 0
	v_addc_co_u32_e32 v67, vcc, 0, v53, vcc
	s_add_i32 s10, s27, 4
	s_add_i32 s27, s27, s28
	s_waitcnt vmcnt(4)
	ds_write_b128 v166, v[0:3]
	v_lshlrev_b32_e32 v0, 8, v20
	v_and_b32_e32 v1, 0x70, v40
	v_bitop3_b32 v0, v27, v0, v1 bitop3:0xde
	v_add_u32_e32 v168, 0, v0
	v_lshlrev_b32_e32 v0, 8, v22
	v_bitop3_b32 v0, v0, v27, v1 bitop3:0xf6
	v_lshlrev_b32_e32 v1, 4, v24
	v_add_u32_e32 v169, 0, v0
	v_lshlrev_b32_e32 v0, 7, v24
	v_and_b32_e32 v1, 0x70, v1
	v_bitop3_b32 v75, v1, v0, v96 bitop3:0xde
	s_waitcnt vmcnt(3)
	ds_write_b128 v167, v[4:7]
	s_waitcnt vmcnt(2)
	ds_write_b128 v168, v[8:11] offset:32768
	v_add_u32_e32 v0, s12, v75
	v_lshlrev_b32_e32 v8, 8, v158
	s_waitcnt vmcnt(1)
	ds_write_b128 v169, v[12:15] offset:32768
	s_waitcnt vmcnt(0)
	ds_write_b128 v0, v[16:19]
	v_bitop3_b32 v0, v130, v8, v96 bitop3:0xde
	v_add_u32_e32 v170, 0, v0
	s_waitcnt lgkmcnt(0)
	s_barrier
	ds_read_b128 v[0:3], v170 offset:32768
	ds_read_b128 v[4:7], v170 offset:40960
	s_waitcnt lgkmcnt(1)
	v_mfma_f32_32x32x16_bf16 v[32:47], v[0:3], v[126:129], 0
	v_bitop3_b32 v0, v58, v8, v96 bitop3:0xde
	v_add_u32_e32 v171, 0, v0
	v_add_u32_e32 v187, 0, v75
	v_add_u32_e32 v188, 0x12000, v187
	s_waitcnt lgkmcnt(0)
	v_mfma_f32_32x32x16_bf16 v[16:31], v[4:7], v[126:129], 0
	ds_read_b128 v[0:3], v171 offset:32768
	ds_read_b128 v[4:7], v171 offset:40960
	s_waitcnt lgkmcnt(1)
	v_mfma_f32_32x32x16_bf16 v[32:47], v[0:3], v[122:125], v[32:47]
	v_bitop3_b32 v0, v59, v8, v96 bitop3:0xde
	v_add_u32_e32 v172, 0, v0
	s_waitcnt lgkmcnt(0)
	v_mfma_f32_32x32x16_bf16 v[16:31], v[4:7], v[122:125], v[16:31]
	ds_read_b128 v[0:3], v172 offset:32768
	ds_read_b128 v[4:7], v172 offset:40960
	s_waitcnt lgkmcnt(1)
	v_mfma_f32_32x32x16_bf16 v[32:47], v[0:3], v[118:121], v[32:47]
	v_bitop3_b32 v0, v62, v8, v96 bitop3:0xde
	v_add_u32_e32 v173, 0, v0
	s_waitcnt lgkmcnt(0)
	v_mfma_f32_32x32x16_bf16 v[16:31], v[4:7], v[118:121], v[16:31]
	ds_read_b128 v[0:3], v173 offset:32768
	ds_read_b128 v[4:7], v173 offset:40960
	s_waitcnt lgkmcnt(1)
	v_mfma_f32_32x32x16_bf16 v[32:47], v[0:3], v[114:117], v[32:47]
	v_or_b32_e32 v0, 0x80, v130
	v_bitop3_b32 v0, v0, v8, v96 bitop3:0xde
	v_add_u32_e32 v174, 0, v0
	s_waitcnt lgkmcnt(0)
	v_mfma_f32_32x32x16_bf16 v[16:31], v[4:7], v[114:117], v[16:31]
	ds_read_b128 v[0:3], v174 offset:32768
	ds_read_b128 v[4:7], v174 offset:40960
	s_waitcnt lgkmcnt(1)
	v_mfma_f32_32x32x16_bf16 v[32:47], v[0:3], v[110:113], v[32:47]
	v_or_b32_e32 v0, 0xa0, v130
	v_bitop3_b32 v0, v0, v8, v96 bitop3:0xde
	v_add_u32_e32 v175, 0, v0
	s_waitcnt lgkmcnt(0)
	v_mfma_f32_32x32x16_bf16 v[16:31], v[4:7], v[110:113], v[16:31]
	ds_read_b128 v[0:3], v175 offset:32768
	ds_read_b128 v[4:7], v175 offset:40960
	s_waitcnt lgkmcnt(1)
	v_mfma_f32_32x32x16_bf16 v[32:47], v[0:3], v[106:109], v[32:47]
	v_or_b32_e32 v0, 0xc0, v130
	v_bitop3_b32 v0, v0, v8, v96 bitop3:0xde
	v_add_u32_e32 v176, 0, v0
	s_waitcnt lgkmcnt(0)
	v_mfma_f32_32x32x16_bf16 v[16:31], v[4:7], v[106:109], v[16:31]
	ds_read_b128 v[0:3], v176 offset:32768
	ds_read_b128 v[4:7], v176 offset:40960
	s_waitcnt lgkmcnt(1)
	v_mfma_f32_32x32x16_bf16 v[32:47], v[0:3], v[102:105], v[32:47]
	v_or_b32_e32 v0, 0xe0, v130
	v_bitop3_b32 v0, v0, v8, v96 bitop3:0xde
	v_add_u32_e32 v177, 0, v0
	s_waitcnt lgkmcnt(0)
	v_mfma_f32_32x32x16_bf16 v[16:31], v[4:7], v[102:105], v[16:31]
	ds_read_b128 v[0:3], v177 offset:32768
	ds_read_b128 v[4:7], v177 offset:40960
	s_waitcnt lgkmcnt(1)
	v_mfma_f32_32x32x16_bf16 v[32:47], v[0:3], v[98:101], v[32:47]
	s_waitcnt lgkmcnt(0)
	v_mfma_f32_32x32x16_bf16 v[16:31], v[4:7], v[98:101], v[16:31]
	ds_read_b128 v[0:3], v179
	ds_read_b128 v[4:7], v163
	ds_read_b128 v[8:11], v179 offset:4096
	ds_read_b128 v[12:15], v163 offset:1024
	s_waitcnt lgkmcnt(2)
	v_mfma_f32_32x32x16_bf16 v[32:47], v[0:3], v[4:7], v[32:47]
	ds_read_b128 v[0:3], v181
	s_waitcnt lgkmcnt(2)
	v_mfma_f32_32x32x16_bf16 v[16:31], v[8:11], v[4:7], v[16:31]
	v_lshlrev_b32_e32 v8, 3, v131
	v_and_b32_e32 v4, 0xc0, v57
	v_and_or_b32 v9, v8, 24, v4
	ds_read_b128 v[4:7], v181 offset:4096
	s_waitcnt lgkmcnt(0)
	v_mfma_f32_32x32x16_bf16 v[16:31], v[4:7], v[12:15], v[16:31]
	ds_read_b128 v[4:7], v163 offset:2048
	v_mfma_f32_32x32x16_bf16 v[32:47], v[0:3], v[12:15], v[32:47]
	v_lshlrev_b32_e32 v0, 1, v56
	v_and_b32_e32 v0, 32, v0
	v_and_b32_e32 v1, 0x100, v8
	v_or3_b32 v57, v9, v0, v1
	ds_read_b128 v[0:3], v183
	ds_read_b128 v[8:11], v183 offset:4096
	ds_read_b128 v[58:61], v163 offset:3072
	ds_read_b128 v[62:65], v185 offset:4096
	s_waitcnt lgkmcnt(3)
	v_mfma_f32_32x32x16_bf16 v[32:47], v[0:3], v[4:7], v[32:47]
	ds_read_b128 v[0:3], v185
	v_add_u32_e32 v164, s3, v57
	s_waitcnt lgkmcnt(3)
	v_mfma_f32_32x32x16_bf16 v[16:31], v[8:11], v[4:7], v[16:31]
	s_waitcnt lgkmcnt(0)
	v_mfma_f32_32x32x16_bf16 v[32:47], v[0:3], v[58:61], v[32:47]
	v_mov_b64_e32 v[0:1], s[80:81]
	v_mov_b64_e32 v[14:15], s[94:95]
	v_mov_b64_e32 v[2:3], s[82:83]
	v_mov_b64_e32 v[4:5], s[84:85]
	v_mov_b64_e32 v[6:7], s[86:87]
	v_mov_b64_e32 v[8:9], s[88:89]
	v_mov_b64_e32 v[10:11], s[90:91]
	v_mfma_f32_32x32x16_bf16 v[16:31], v[62:65], v[58:61], v[16:31]
	s_nop 3
	v_max_f32_e32 v58, v33, v33
	v_max_f32_e32 v59, v32, v32
	v_max_f32_e32 v58, v59, v58
	v_max3_f32 v74, v58, v34, v35
	v_lshl_add_u64 v[58:59], v[52:53], 0, s[16:17]
	s_mov_b64 s[16:17], 0x60000
	v_lshl_add_u64 v[62:63], v[52:53], 0, s[16:17]
	v_add_co_u32_e32 v52, vcc, s2, v52
	s_movk_i32 s2, 0x2000
	s_nop 0
	v_addc_co_u32_e32 v53, vcc, 0, v53, vcc
	global_load_dwordx4 v[58:61], v[58:59], off offset:256
	s_nop 0
	global_load_dwordx4 v[62:65], v[62:63], off offset:256
	s_nop 0
	global_load_dwordx4 v[66:69], v[66:67], off
	s_nop 0
	global_load_dwordx4 v[70:73], v[52:53], off
	v_add_co_u32_e32 v52, vcc, s2, v54
	v_max3_f32 v74, v74, v36, v37
	s_nop 0
	v_addc_co_u32_e32 v53, vcc, 0, v55, vcc
	global_load_dwordx4 v[52:55], v[52:53], off
	v_max3_f32 v74, v74, v38, v39
	v_max3_f32 v74, v74, v40, v41
	v_max3_f32 v74, v74, v42, v43
	v_max3_f32 v74, v74, v44, v45
	v_max3_f32 v74, v74, v46, v47
	v_max3_f32 v74, v74, v16, v17
	v_max3_f32 v74, v74, v18, v19
	v_max3_f32 v74, v74, v20, v21
	v_max3_f32 v74, v74, v22, v23
	v_max3_f32 v74, v74, v24, v25
	v_max3_f32 v74, v74, v26, v27
	v_max3_f32 v74, v74, v28, v29
	v_max3_f32 v74, v74, v30, v31
	v_mov_b32_e32 v76, v74
	s_nop 1
	v_permlane32_swap_b32_e32 v74, v76
	v_max_f32_e32 v76, v76, v76
	v_max_f32_e32 v74, v74, v74
	v_max_f32_e32 v74, v74, v76
	v_add_f32_e32 v76, 0x7149f2ca, v74
	v_max_f32_e32 v74, 0xf149f2ca, v74
	v_cmp_ge_f32_e32 vcc, s21, v76
	v_sub_f32_e32 v76, 0xf149f2ca, v74
	v_mul_f32_e32 v76, 0x3dd53b94, v76
	v_exp_f32_e32 v76, v76
	s_cmp_eq_u64 vcc, exec
	s_cselect_b64 vcc, -1, 0
	v_cndmask_b32_e32 v165, v74, v207, vcc
	v_mul_f32_e32 v74, 0xbdd53b94, v165
	s_addk_i32 s3, 0x4000
	v_cndmask_b32_e64 v186, v76, 1.0, vcc
	v_mov_b32_e32 v76, v74
	v_pk_fma_f32 v[148:149], v[16:17], s[74:75], v[74:75] op_sel_hi:[1,0,0]
	v_add_u32_e32 v162, s3, v57
	v_and_b32_e32 v16, 7, v56
	v_readlane_b32 s2, v253, 11
	v_fmamk_f32 v32, v32, 0x3dd53b94, v74
	v_fmamk_f32 v33, v33, 0x3dd53b94, v74
	v_fmamk_f32 v34, v34, 0x3dd53b94, v74
	v_fmamk_f32 v35, v35, 0x3dd53b94, v74
	v_fmamk_f32 v36, v36, 0x3dd53b94, v74
	v_fmamk_f32 v37, v37, 0x3dd53b94, v74
	v_fmamk_f32 v38, v38, 0x3dd53b94, v74
	v_fmamk_f32 v39, v39, 0x3dd53b94, v74
	v_fmamk_f32 v40, v40, 0x3dd53b94, v74
	v_fmamk_f32 v41, v41, 0x3dd53b94, v74
	v_fmamk_f32 v42, v42, 0x3dd53b94, v74
	v_fmamk_f32 v43, v43, 0x3dd53b94, v74
	v_fmamk_f32 v44, v44, 0x3dd53b94, v74
	v_fmamk_f32 v45, v45, 0x3dd53b94, v74
	v_fmamk_f32 v46, v46, 0x3dd53b94, v74
	v_fmac_f32_e32 v76, 0x3dd53b94, v47
	v_lshl_or_b32 v50, v16, 4, v50
	v_readlane_b32 s3, v253, 12
	v_exp_f32_e32 v220, v32
	v_exp_f32_e32 v222, v33
	v_exp_f32_e32 v218, v34
	v_exp_f32_e32 v221, v35
	v_exp_f32_e32 v216, v36
	v_exp_f32_e32 v219, v37
	v_exp_f32_e32 v215, v38
	v_exp_f32_e32 v217, v39
	v_exp_f32_e32 v212, v40
	v_exp_f32_e32 v214, v41
	v_exp_f32_e32 v210, v42
	v_exp_f32_e32 v213, v43
	v_exp_f32_e32 v198, v44
	v_exp_f32_e32 v211, v45
	v_exp_f32_e32 v197, v46
	v_exp_f32_e32 v199, v76
	v_lshl_add_u64 v[132:133], s[2:3], 0, v[50:51]
	v_and_b32_e32 v16, 15, v56
	v_readlane_b32 s2, v253, 15
	s_waitcnt vmcnt(0)
	v_lshl_or_b32 v48, v16, 4, v48
	v_readlane_b32 s3, v253, 16
	v_mov_b64_e32 v[12:13], s[92:93]
	v_readlane_b32 s88, v254, 6
	v_readlane_b32 s90, v254, 4
	v_readlane_b32 s86, v254, 2
	v_readlane_b32 s92, v253, 57
	v_pk_fma_f32 v[142:143], v[30:31], s[74:75], v[74:75] op_sel_hi:[1,0,0]
	v_pk_fma_f32 v[150:151], v[28:29], s[74:75], v[74:75] op_sel_hi:[1,0,0]
	v_pk_fma_f32 v[152:153], v[26:27], s[74:75], v[74:75] op_sel_hi:[1,0,0]
	v_pk_fma_f32 v[138:139], v[24:25], s[74:75], v[74:75] op_sel_hi:[1,0,0]
	v_pk_fma_f32 v[140:141], v[22:23], s[74:75], v[74:75] op_sel_hi:[1,0,0]
	v_pk_fma_f32 v[144:145], v[20:21], s[74:75], v[74:75] op_sel_hi:[1,0,0]
	v_pk_fma_f32 v[146:147], v[18:19], s[74:75], v[74:75] op_sel_hi:[1,0,0]
	s_waitcnt vmcnt(4)
	ds_write_b128 v166, v[58:61] offset:16384
	s_waitcnt vmcnt(3)
	ds_write_b128 v167, v[62:65] offset:16384
	s_waitcnt vmcnt(2)
	ds_write_b128 v168, v[66:69] offset:49152
	s_waitcnt vmcnt(1)
	ds_write_b128 v169, v[70:73] offset:49152
	s_waitcnt vmcnt(0)
	ds_write_b128 v188, v[52:55]
	v_lshl_add_u64 v[134:135], s[2:3], 0, v[48:49]
	v_mov_b64_e32 v[62:63], v[14:15]
	v_mov_b64_e32 v[46:47], v[14:15]
	v_mov_b64_e32 v[30:31], v[14:15]
	s_mov_b64 s[82:83], 0x5000
	s_movk_i32 s85, 0x3000
	s_mov_b32 s84, 0x18000
	v_readlane_b32 s94, v254, 10
	v_readlane_b32 s89, v254, 7
	v_readlane_b32 s91, v254, 5
	v_readlane_b32 s87, v254, 3
	v_readlane_b32 s93, v253, 58
	v_readlane_b32 s95, v253, 54
	v_mov_b64_e32 v[60:61], v[12:13]
	v_mov_b64_e32 v[58:59], v[10:11]
	v_mov_b64_e32 v[56:57], v[8:9]
	v_mov_b64_e32 v[54:55], v[6:7]
	v_mov_b64_e32 v[52:53], v[4:5]
	v_mov_b64_e32 v[50:51], v[2:3]
	v_mov_b64_e32 v[48:49], v[0:1]
	v_mov_b64_e32 v[44:45], v[12:13]
	v_mov_b64_e32 v[42:43], v[10:11]
	v_mov_b64_e32 v[40:41], v[8:9]
	v_mov_b64_e32 v[38:39], v[6:7]
	v_mov_b64_e32 v[36:37], v[4:5]
	v_mov_b64_e32 v[34:35], v[2:3]
	v_mov_b64_e32 v[32:33], v[0:1]
	v_mov_b64_e32 v[28:29], v[12:13]
	v_mov_b64_e32 v[26:27], v[10:11]
	v_mov_b64_e32 v[24:25], v[8:9]
	v_mov_b64_e32 v[22:23], v[6:7]
	v_mov_b64_e32 v[20:21], v[4:5]
	v_mov_b64_e32 v[18:19], v[2:3]
	v_mov_b64_e32 v[16:17], v[0:1]
	s_waitcnt lgkmcnt(0)
	s_barrier
	v_mbcnt_lo_u32_b32 v64, -1, 0
	v_mbcnt_hi_u32_b32 v64, -1, v64
	s_and_b32 s2, s78, 1
	s_lshl_b32 s3, s2, 2
	v_lshrrev_b32_e32 v65, 4, v64
	v_and_b32_e32 v66, 15, v64
	v_add_u32_e32 v67, s3, v65
	v_xor_b32_e32 v66, v66, v67
	v_lshlrev_b32_e32 v66, 4, v66
	v_lshl_add_u32 v166, v65, 12, v66
	v_lshrrev_b32_e32 v65, 3, v64
	v_and_b32_e32 v66, 7, v64
	v_xor_b32_e32 v66, v66, v65
	v_lshlrev_b32_e32 v66, 4, v66
	v_lshl_add_u32 v168, v65, 7, v66
	v_bfe_u32 v65, v64, 4, 1
	v_bfe_u32 v66, v64, 2, 2
	v_lshl_add_u32 v65, v65, 3, v66
	v_lshrrev_b32_e32 v66, 5, v64
	v_and_b32_e32 v67, 3, v64
	v_lshlrev_b32_e32 v67, 4, v67
	v_lshl_add_u32 v66, v66, 6, v67
	v_lshl_add_u32 v167, v65, 12, v66
	s_bfe_u32 s2, s78, 0x10002
	s_lshl_b32 s2, s2, 16
	s_bfe_u32 s3, s78, 0x10001
	s_lshl_b32 s3, s3, 14
	s_add_u32 s2, s2, s3
	s_and_b32 s3, s78, 1
	s_lshl_b32 s3, s3, 7
	s_add_u32 s2, s2, s3
	v_add_u32_e32 v167, s2, v167
	.p2align 6

.LBB0_751:
	v_max_f32_e32 v84, v84, v84
	v_max_f32_e32 v85, v165, v165
	v_max_f32_e32 v84, v85, v84
	v_sub_f32_e32 v85, v165, v84
	v_mul_f32_e32 v85, 0x3dd53b94, v85
	v_exp_f32_e32 v195, v85
	v_mul_f32_e32 v136, 0xbdd53b94, v84
	v_mov_b32_e32 v165, v84
	s_branch .LBB0_744
	.p2align 6

.LBB0_1037:
	s_ashr_i32 s53, s52, 31
	s_lshl_b64 s[34:35], s[52:53], 20
	s_add_u32 s68, s50, s34
	s_addc_u32 s69, s51, s35
	s_and_b64 s[34:35], s[42:43], exec
	s_cselect_b32 s10, s69, s45
	s_cselect_b32 s12, s68, s44
	s_ashr_i32 s31, s30, 31
	s_lshl_b64 s[34:35], s[30:31], 20
	s_add_u32 s82, s46, s34
	s_addc_u32 s83, s47, s35
	s_and_b64 s[34:35], s[42:43], exec
	s_cselect_b32 s18, s83, s85
	s_cselect_b32 s20, s82, s84
	s_add_u32 s44, s44, 0x80080
	s_addc_u32 s45, s45, 0
	s_add_u32 s28, s84, 0x100
	v_mov_b32_e32 v0, 0
	s_addc_u32 s31, s85, 0
	s_mov_b32 s33, -2
	v_mov_b32_e32 v1, v0
	v_mov_b32_e32 v2, v0
	v_mov_b32_e32 v3, v0
	v_mov_b32_e32 v4, v0
	v_mov_b32_e32 v5, v0
	v_mov_b32_e32 v6, v0
	v_mov_b32_e32 v7, v0
	v_mov_b32_e32 v16, v0
	v_mov_b32_e32 v17, v0
	v_mov_b32_e32 v18, v0
	v_mov_b32_e32 v19, v0
	v_mov_b32_e32 v20, v0
	v_mov_b32_e32 v21, v0
	v_mov_b32_e32 v22, v0
	v_mov_b32_e32 v23, v0
	v_mov_b32_e32 v32, v0
	v_mov_b32_e32 v33, v0
	v_mov_b32_e32 v34, v0
	v_mov_b32_e32 v35, v0
	v_mov_b32_e32 v36, v0
	v_mov_b32_e32 v37, v0
	v_mov_b32_e32 v38, v0
	v_mov_b32_e32 v39, v0
	v_mov_b32_e32 v48, v0
	v_mov_b32_e32 v49, v0
	v_mov_b32_e32 v50, v0
	v_mov_b32_e32 v51, v0
	v_mov_b32_e32 v52, v0
	v_mov_b32_e32 v53, v0
	v_mov_b32_e32 v54, v0
	v_mov_b32_e32 v55, v0
	v_mov_b32_e32 v8, v0
	v_mov_b32_e32 v9, v0
	v_mov_b32_e32 v10, v0
	v_mov_b32_e32 v11, v0
	v_mov_b32_e32 v12, v0
	v_mov_b32_e32 v13, v0
	v_mov_b32_e32 v14, v0
	v_mov_b32_e32 v15, v0
	v_mov_b32_e32 v24, v0
	v_mov_b32_e32 v25, v0
	v_mov_b32_e32 v26, v0
	v_mov_b32_e32 v27, v0
	v_mov_b32_e32 v28, v0
	v_mov_b32_e32 v29, v0
	v_mov_b32_e32 v30, v0
	v_mov_b32_e32 v31, v0
	v_mov_b32_e32 v40, v0
	v_mov_b32_e32 v41, v0
	v_mov_b32_e32 v42, v0
	v_mov_b32_e32 v43, v0
	v_mov_b32_e32 v44, v0
	v_mov_b32_e32 v45, v0
	v_mov_b32_e32 v46, v0
	v_mov_b32_e32 v47, v0
	v_mov_b32_e32 v56, v0
	v_mov_b32_e32 v57, v0
	v_mov_b32_e32 v58, v0
	v_mov_b32_e32 v59, v0
	v_mov_b32_e32 v60, v0
	v_mov_b32_e32 v61, v0
	v_mov_b32_e32 v62, v0
	v_mov_b32_e32 v63, v0
	v_mov_b32_e32 v64, v0
	v_mov_b32_e32 v65, v0
	v_mov_b32_e32 v66, v0
	v_mov_b32_e32 v67, v0
	v_mov_b32_e32 v68, v0
	v_mov_b32_e32 v69, v0
	v_mov_b32_e32 v70, v0
	v_mov_b32_e32 v71, v0
	v_mov_b32_e32 v80, v0
	v_mov_b32_e32 v81, v0
	v_mov_b32_e32 v82, v0
	v_mov_b32_e32 v83, v0
	v_mov_b32_e32 v84, v0
	v_mov_b32_e32 v85, v0
	v_mov_b32_e32 v86, v0
	v_mov_b32_e32 v87, v0
	v_mov_b32_e32 v98, v0
	v_mov_b32_e32 v99, v0
	v_mov_b32_e32 v100, v0
	v_mov_b32_e32 v101, v0
	v_mov_b32_e32 v102, v0
	v_mov_b32_e32 v103, v0
	v_mov_b32_e32 v104, v0
	v_mov_b32_e32 v105, v0
	v_mov_b32_e32 v114, v0
	v_mov_b32_e32 v115, v0
	v_mov_b32_e32 v116, v0
	v_mov_b32_e32 v117, v0
	v_mov_b32_e32 v118, v0
	v_mov_b32_e32 v119, v0
	v_mov_b32_e32 v120, v0
	v_mov_b32_e32 v121, v0
	v_mov_b32_e32 v72, v0
	v_mov_b32_e32 v73, v0
	v_mov_b32_e32 v74, v0
	v_mov_b32_e32 v75, v0
	v_mov_b32_e32 v76, v0
	v_mov_b32_e32 v77, v0
	v_mov_b32_e32 v78, v0
	v_mov_b32_e32 v79, v0
	v_mov_b32_e32 v88, v0
	v_mov_b32_e32 v89, v0
	v_mov_b32_e32 v90, v0
	v_mov_b32_e32 v91, v0
	v_mov_b32_e32 v92, v0
	v_mov_b32_e32 v93, v0
	v_mov_b32_e32 v94, v0
	v_mov_b32_e32 v95, v0
	v_mov_b32_e32 v106, v0
	v_mov_b32_e32 v107, v0
	v_mov_b32_e32 v108, v0
	v_mov_b32_e32 v109, v0
	v_mov_b32_e32 v110, v0
	v_mov_b32_e32 v111, v0
	v_mov_b32_e32 v112, v0
	v_mov_b32_e32 v113, v0
	v_mov_b32_e32 v122, v0
	v_mov_b32_e32 v123, v0
	v_mov_b32_e32 v124, v0
	v_mov_b32_e32 v125, v0
	v_mov_b32_e32 v126, v0
	v_mov_b32_e32 v127, v0
	v_mov_b32_e32 v128, v0
	v_mov_b32_e32 v129, v0
	v_add_u32_e32 v165, 0x80, v96
	v_add_u32_e32 v223, 0x80, v142
	v_add_u32_e32 v225, 0x80, v146
	v_add_u32_e32 v227, 0x80, v144
	.p2align 6

.LBB0_1264:
	s_ashr_i32 s17, s16, 31
	s_lshl_b64 s[24:25], s[16:17], 22
	s_add_u32 s24, s51, s24
	s_addc_u32 s25, s58, s25
	s_and_b64 s[30:31], s[40:41], exec
	s_cselect_b32 s12, s25, s43
	s_cselect_b32 s17, s24, s42
	s_ashr_i32 s5, s4, 31
	s_lshl_b64 s[30:31], s[4:5], 22
	s_add_u32 s30, s27, s30
	s_addc_u32 s31, s50, s31
	s_and_b64 s[52:53], s[40:41], exec
	s_cselect_b32 s5, s31, s45
	s_cselect_b32 s18, s30, s44
	s_add_u32 s42, s42, 0x200080
	s_addc_u32 s43, s43, 0
	s_add_u32 s20, s44, 0x100
	v_mov_b32_e32 v0, 0
	s_addc_u32 s28, s45, 0
	s_mov_b32 s33, -2
	v_mov_b32_e32 v1, v0
	v_mov_b32_e32 v2, v0
	v_mov_b32_e32 v3, v0
	v_mov_b32_e32 v4, v0
	v_mov_b32_e32 v5, v0
	v_mov_b32_e32 v6, v0
	v_mov_b32_e32 v7, v0
	v_mov_b32_e32 v16, v0
	v_mov_b32_e32 v17, v0
	v_mov_b32_e32 v18, v0
	v_mov_b32_e32 v19, v0
	v_mov_b32_e32 v20, v0
	v_mov_b32_e32 v21, v0
	v_mov_b32_e32 v22, v0
	v_mov_b32_e32 v23, v0
	v_mov_b32_e32 v32, v0
	v_mov_b32_e32 v33, v0
	v_mov_b32_e32 v34, v0
	v_mov_b32_e32 v35, v0
	v_mov_b32_e32 v36, v0
	v_mov_b32_e32 v37, v0
	v_mov_b32_e32 v38, v0
	v_mov_b32_e32 v39, v0
	v_mov_b32_e32 v48, v0
	v_mov_b32_e32 v49, v0
	v_mov_b32_e32 v50, v0
	v_mov_b32_e32 v51, v0
	v_mov_b32_e32 v52, v0
	v_mov_b32_e32 v53, v0
	v_mov_b32_e32 v54, v0
	v_mov_b32_e32 v55, v0
	v_mov_b32_e32 v8, v0
	v_mov_b32_e32 v9, v0
	v_mov_b32_e32 v10, v0
	v_mov_b32_e32 v11, v0
	v_mov_b32_e32 v12, v0
	v_mov_b32_e32 v13, v0
	v_mov_b32_e32 v14, v0
	v_mov_b32_e32 v15, v0
	v_mov_b32_e32 v24, v0
	v_mov_b32_e32 v25, v0
	v_mov_b32_e32 v26, v0
	v_mov_b32_e32 v27, v0
	v_mov_b32_e32 v28, v0
	v_mov_b32_e32 v29, v0
	v_mov_b32_e32 v30, v0
	v_mov_b32_e32 v31, v0
	v_mov_b32_e32 v40, v0
	v_mov_b32_e32 v41, v0
	v_mov_b32_e32 v42, v0
	v_mov_b32_e32 v43, v0
	v_mov_b32_e32 v44, v0
	v_mov_b32_e32 v45, v0
	v_mov_b32_e32 v46, v0
	v_mov_b32_e32 v47, v0
	v_mov_b32_e32 v56, v0
	v_mov_b32_e32 v57, v0
	v_mov_b32_e32 v58, v0
	v_mov_b32_e32 v59, v0
	v_mov_b32_e32 v60, v0
	v_mov_b32_e32 v61, v0
	v_mov_b32_e32 v62, v0
	v_mov_b32_e32 v63, v0
	v_mov_b32_e32 v64, v0
	v_mov_b32_e32 v65, v0
	v_mov_b32_e32 v66, v0
	v_mov_b32_e32 v67, v0
	v_mov_b32_e32 v68, v0
	v_mov_b32_e32 v69, v0
	v_mov_b32_e32 v70, v0
	v_mov_b32_e32 v71, v0
	v_mov_b32_e32 v80, v0
	v_mov_b32_e32 v81, v0
	v_mov_b32_e32 v82, v0
	v_mov_b32_e32 v83, v0
	v_mov_b32_e32 v84, v0
	v_mov_b32_e32 v85, v0
	v_mov_b32_e32 v86, v0
	v_mov_b32_e32 v87, v0
	v_mov_b32_e32 v98, v0
	v_mov_b32_e32 v99, v0
	v_mov_b32_e32 v100, v0
	v_mov_b32_e32 v101, v0
	v_mov_b32_e32 v102, v0
	v_mov_b32_e32 v103, v0
	v_mov_b32_e32 v104, v0
	v_mov_b32_e32 v105, v0
	v_mov_b32_e32 v114, v0
	v_mov_b32_e32 v115, v0
	v_mov_b32_e32 v116, v0
	v_mov_b32_e32 v117, v0
	v_mov_b32_e32 v118, v0
	v_mov_b32_e32 v119, v0
	v_mov_b32_e32 v120, v0
	v_mov_b32_e32 v121, v0
	v_mov_b32_e32 v72, v0
	v_mov_b32_e32 v73, v0
	v_mov_b32_e32 v74, v0
	v_mov_b32_e32 v75, v0
	v_mov_b32_e32 v76, v0
	v_mov_b32_e32 v77, v0
	v_mov_b32_e32 v78, v0
	v_mov_b32_e32 v79, v0
	v_mov_b32_e32 v88, v0
	v_mov_b32_e32 v89, v0
	v_mov_b32_e32 v90, v0
	v_mov_b32_e32 v91, v0
	v_mov_b32_e32 v92, v0
	v_mov_b32_e32 v93, v0
	v_mov_b32_e32 v94, v0
	v_mov_b32_e32 v95, v0
	v_mov_b32_e32 v106, v0
	v_mov_b32_e32 v107, v0
	v_mov_b32_e32 v108, v0
	v_mov_b32_e32 v109, v0
	v_mov_b32_e32 v110, v0
	v_mov_b32_e32 v111, v0
	v_mov_b32_e32 v112, v0
	v_mov_b32_e32 v113, v0
	v_mov_b32_e32 v122, v0
	v_mov_b32_e32 v123, v0
	v_mov_b32_e32 v124, v0
	v_mov_b32_e32 v125, v0
	v_mov_b32_e32 v126, v0
	v_mov_b32_e32 v127, v0
	v_mov_b32_e32 v128, v0
	v_mov_b32_e32 v129, v0
	v_add_u32_e32 v222, 0x80, v96
	v_add_u32_e32 v223, 0x80, v134
	v_add_u32_e32 v224, 0x80, v138
	v_add_u32_e32 v225, 0x80, v136
	v_add_u32_e32 v226, 0x200000, v138
	v_add_u32_e32 v227, 0x200000, v136
	.p2align 6

.LBB0_1283:
	s_ashr_i32 s25, s24, 31
	s_lshl_b64 s[30:31], s[24:25], 20
	s_add_u32 s30, s10, s30
	s_addc_u32 s31, s27, s31
	s_and_b64 s[38:39], s[42:43], exec
	s_cselect_b32 s3, s31, s53
	s_cselect_b32 s12, s30, s52
	s_ashr_i32 s17, s16, 31
	s_lshl_b64 s[38:39], s[16:17], 20
	s_add_u32 s44, s14, s38
	s_addc_u32 s45, s26, s39
	s_and_b64 s[38:39], s[42:43], exec
	s_cselect_b32 s17, s45, s69
	s_cselect_b32 s18, s44, s68
	s_add_u32 s52, s52, 0x80080
	s_addc_u32 s53, s53, 0
	s_add_u32 s20, s68, 0x100
	v_mov_b32_e32 v0, 0
	s_addc_u32 s25, s69, 0
	s_mov_b32 s28, -2
	v_mov_b32_e32 v1, v0
	v_mov_b32_e32 v2, v0
	v_mov_b32_e32 v3, v0
	v_mov_b32_e32 v4, v0
	v_mov_b32_e32 v5, v0
	v_mov_b32_e32 v6, v0
	v_mov_b32_e32 v7, v0
	v_mov_b32_e32 v16, v0
	v_mov_b32_e32 v17, v0
	v_mov_b32_e32 v18, v0
	v_mov_b32_e32 v19, v0
	v_mov_b32_e32 v20, v0
	v_mov_b32_e32 v21, v0
	v_mov_b32_e32 v22, v0
	v_mov_b32_e32 v23, v0
	v_mov_b32_e32 v32, v0
	v_mov_b32_e32 v33, v0
	v_mov_b32_e32 v34, v0
	v_mov_b32_e32 v35, v0
	v_mov_b32_e32 v36, v0
	v_mov_b32_e32 v37, v0
	v_mov_b32_e32 v38, v0
	v_mov_b32_e32 v39, v0
	v_mov_b32_e32 v48, v0
	v_mov_b32_e32 v49, v0
	v_mov_b32_e32 v50, v0
	v_mov_b32_e32 v51, v0
	v_mov_b32_e32 v52, v0
	v_mov_b32_e32 v53, v0
	v_mov_b32_e32 v54, v0
	v_mov_b32_e32 v55, v0
	v_mov_b32_e32 v8, v0
	v_mov_b32_e32 v9, v0
	v_mov_b32_e32 v10, v0
	v_mov_b32_e32 v11, v0
	v_mov_b32_e32 v12, v0
	v_mov_b32_e32 v13, v0
	v_mov_b32_e32 v14, v0
	v_mov_b32_e32 v15, v0
	v_mov_b32_e32 v24, v0
	v_mov_b32_e32 v25, v0
	v_mov_b32_e32 v26, v0
	v_mov_b32_e32 v27, v0
	v_mov_b32_e32 v28, v0
	v_mov_b32_e32 v29, v0
	v_mov_b32_e32 v30, v0
	v_mov_b32_e32 v31, v0
	v_mov_b32_e32 v40, v0
	v_mov_b32_e32 v41, v0
	v_mov_b32_e32 v42, v0
	v_mov_b32_e32 v43, v0
	v_mov_b32_e32 v44, v0
	v_mov_b32_e32 v45, v0
	v_mov_b32_e32 v46, v0
	v_mov_b32_e32 v47, v0
	v_mov_b32_e32 v56, v0
	v_mov_b32_e32 v57, v0
	v_mov_b32_e32 v58, v0
	v_mov_b32_e32 v59, v0
	v_mov_b32_e32 v60, v0
	v_mov_b32_e32 v61, v0
	v_mov_b32_e32 v62, v0
	v_mov_b32_e32 v63, v0
	v_mov_b32_e32 v64, v0
	v_mov_b32_e32 v65, v0
	v_mov_b32_e32 v66, v0
	v_mov_b32_e32 v67, v0
	v_mov_b32_e32 v68, v0
	v_mov_b32_e32 v69, v0
	v_mov_b32_e32 v70, v0
	v_mov_b32_e32 v71, v0
	v_mov_b32_e32 v80, v0
	v_mov_b32_e32 v81, v0
	v_mov_b32_e32 v82, v0
	v_mov_b32_e32 v83, v0
	v_mov_b32_e32 v84, v0
	v_mov_b32_e32 v85, v0
	v_mov_b32_e32 v86, v0
	v_mov_b32_e32 v87, v0
	v_mov_b32_e32 v98, v0
	v_mov_b32_e32 v99, v0
	v_mov_b32_e32 v100, v0
	v_mov_b32_e32 v101, v0
	v_mov_b32_e32 v102, v0
	v_mov_b32_e32 v103, v0
	v_mov_b32_e32 v104, v0
	v_mov_b32_e32 v105, v0
	v_mov_b32_e32 v114, v0
	v_mov_b32_e32 v115, v0
	v_mov_b32_e32 v116, v0
	v_mov_b32_e32 v117, v0
	v_mov_b32_e32 v118, v0
	v_mov_b32_e32 v119, v0
	v_mov_b32_e32 v120, v0
	v_mov_b32_e32 v121, v0
	v_mov_b32_e32 v72, v0
	v_mov_b32_e32 v73, v0
	v_mov_b32_e32 v74, v0
	v_mov_b32_e32 v75, v0
	v_mov_b32_e32 v76, v0
	v_mov_b32_e32 v77, v0
	v_mov_b32_e32 v78, v0
	v_mov_b32_e32 v79, v0
	v_mov_b32_e32 v88, v0
	v_mov_b32_e32 v89, v0
	v_mov_b32_e32 v90, v0
	v_mov_b32_e32 v91, v0
	v_mov_b32_e32 v92, v0
	v_mov_b32_e32 v93, v0
	v_mov_b32_e32 v94, v0
	v_mov_b32_e32 v95, v0
	v_mov_b32_e32 v106, v0
	v_mov_b32_e32 v107, v0
	v_mov_b32_e32 v108, v0
	v_mov_b32_e32 v109, v0
	v_mov_b32_e32 v110, v0
	v_mov_b32_e32 v111, v0
	v_mov_b32_e32 v112, v0
	v_mov_b32_e32 v113, v0
	v_mov_b32_e32 v122, v0
	v_mov_b32_e32 v123, v0
	v_mov_b32_e32 v124, v0
	v_mov_b32_e32 v125, v0
	v_mov_b32_e32 v126, v0
	v_mov_b32_e32 v127, v0
	v_mov_b32_e32 v128, v0
	v_mov_b32_e32 v129, v0
	v_add_u32_e32 v145, 0x80, v96
	v_add_u32_e32 v199, 0x80, v134
	v_add_u32_e32 v227, 0x80, v138
	v_add_u32_e32 v229, 0x80, v136
	.p2align 6
